# P6 dense attention: hand-scheduled tile body (K/V fragment prefetch, bfe/bfi mask, fma-folded scale), tile loads one iteration ahead, waves 4-7 in anti-phase; RG-LRU fix-up carry chain batched 16 load
# speedup vs baseline: 1.0081x; 1.0081x over previous
; #define A_GLOAD(t) do { _Pragma("unroll") for (int _i = 0; _i < 2; ++_i) { kst[_i] = *(const u32x4*)(kg + (size_t)((t) * 64 + _i * 32) * 512); vst[_i] = *(const u32x4*)(vg + (size_t)((t) * 64 + _i * 32) * 512); } } while (0)
; #define A_LSTORE(buf) do { _Pragma("unroll") for (int _i = 0; _i < 2; ++_i) { *(PG8_LAS u32x4*)(lds + (buf) * A_STAGE + (srow + _i * 32) * A_KP + sch * 16) = kst[_i]; \
;         *(PG8_LAS u32x4*)(lds + (buf) * A_STAGE + A_KBYTES + (srow + _i * 32) * A_VP + sch * 16) = vst[_i]; } } while (0)
; __device__ __forceinline__ void attn_dense_unit(const Params& p, PG8_LAS unsigned char* lds, int b, int n, int qb) {
;     ...
;     const int q = qb * 128 + wave * 16 + (r & 15), head = 2 * n + (r >> 4);
;     const size_t qrow = (size_t)b * SEQ + q;
;     bf16x8 qf[8];
; #pragma unroll
;     for (int ks = 0; ks < 8; ++ks) qf[ks] = *(const bf16x8*)(QB + qrow * 1024 + head * HD + ks * 16 + kh * 8);
;     f32x16 O[4];
; #pragma unroll
;     for (int dt = 0; dt < 4; ++dt)
; #pragma unroll
;         for (int i = 0; i < 16; ++i) O[dt][i] = 0.f;
;     float m = -INFINITY, l = 0.f;
;     const int ntile = 2 * qb + 2, qmax_w = qb * 128 + wave * 16 + 15;
;     const int srow = tid >> 4, sch = tid & 15;
;     const bf16_t* kg = KB + ((size_t)b * SEQ + srow) * 512 + n * HD + sch * 8;
;     const bf16_t* vg = VB + ((size_t)b * SEQ + srow) * 512 + n * HD + sch * 8;
;     u32x4 kst[2], vst[2];
;     ...
;     A_GLOAD(0); A_LSTORE(0);
;     unsigned long long mw = BM[qrow * 64];
;     __syncthreads();
;     const int i16 = lane & 15, g2 = (lane >> 4) & 1;
;     const int vlane_off = (4 * kh + (i16 >> 2)) * A_VP + (16 * g2 + 4 * (i16 & 3)) * 2;
;     for (int t = 0; t < ntile; ++t) {
;         const bool more = (t + 1 < ntile);
;         if (more) A_GLOAD(t + 1);
.LBB0_2873:
	v_mov_b32_e32 v28, v0
	s_lshl_b32 s12, s43, 10
	v_ashrrev_i32_e32 v18, 4, v28
	s_and_b32 s36, s12, 0x1000
	s_mov_b32 s37, s13
	v_ashrrev_i32_e32 v19, 31, v18
	s_waitcnt vmcnt(0)
	v_lshl_add_u64 v[2:3], v[18:19], 0, s[36:37]
	s_lshl_b32 s12, s43, 8
	v_lshlrev_b64 v[2:3], 10, v[2:3]
	s_and_b32 s44, s12, 0x300
	v_lshl_add_u64 v[4:5], s[8:9], 0, v[2:3]
	s_mov_b32 s45, s13
	v_lshl_add_u64 v[2:3], s[6:7], 0, v[2:3]
	v_lshl_add_u64 v[4:5], v[4:5], 0, s[44:45]
	v_lshl_add_u64 v[2:3], v[2:3], 0, s[44:45]
	s_ashr_i32 s45, s43, 3
	v_readfirstlane_b32 s46, v28
	v_and_b32_e32 v22, 15, v28
	s_sub_i32 s12, 31, s45
	s_lshr_b32 s98, s46, 8
	s_ashr_i32 s46, s46, 2
	v_lshlrev_b32_e32 v20, 4, v22
	v_mov_b32_e32 v21, v147
	s_lshl_b32 s12, s12, 7
	s_and_b32 s46, s46, -16
	v_lshl_add_u64 v[10:11], v[4:5], 0, v[20:21]
	s_add_i32 s46, s46, s12
	v_lshl_add_u64 v[12:13], v[2:3], 0, v[20:21]
	global_load_dwordx4 v[2:5], v[10:11], off
	global_load_dwordx4 v[6:9], v[12:13], off
	v_add_co_u32_e32 v10, vcc, s33, v10
	v_or_b32_e32 v22, s46, v22
	s_nop 0
	v_addc_co_u32_e32 v11, vcc, 0, v11, vcc
	v_ashrrev_i32_e32 v23, 31, v22
	v_lshlrev_b32_e32 v26, 3, v28
	v_add_co_u32_e32 v14, vcc, s33, v12
	v_lshl_add_u64 v[148:149], v[22:23], 0, s[36:37]
	v_and_b32_e32 v26, 0x80, v26
	v_addc_co_u32_e32 v15, vcc, 0, v13, vcc
	v_lshlrev_b64 v[24:25], 11, v[148:149]
	v_or_b32_e32 v150, s44, v26
	global_load_dwordx4 v[10:13], v[10:11], off
	s_nop 0
	global_load_dwordx4 v[14:17], v[14:15], off
	v_bfe_u32 v21, v28, 5, 1
	v_lshl_add_u64 v[24:25], s[4:5], 0, v[24:25]
	v_lshlrev_b32_e32 v146, 1, v150
	v_lshl_add_u64 v[24:25], v[24:25], 0, v[146:147]
	v_lshlrev_b32_e32 v146, 4, v21
	v_lshl_add_u64 v[24:25], v[24:25], 0, v[146:147]
	global_load_dwordx4 v[126:129], v[24:25], off
	global_load_dwordx4 v[122:125], v[24:25], off offset:32
	global_load_dwordx4 v[118:121], v[24:25], off offset:64
	global_load_dwordx4 v[114:117], v[24:25], off offset:96
	global_load_dwordx4 v[106:109], v[24:25], off offset:128
	global_load_dwordx4 v[102:105], v[24:25], off offset:160
	v_lshlrev_b64 v[26:27], 9, v[148:149]
	v_lshl_add_u64 v[26:27], s[10:11], 0, v[26:27]
	global_load_dwordx2 v[158:159], v[26:27], off
	global_load_dwordx4 v[110:113], v[24:25], off offset:192
	global_load_dwordx4 v[98:101], v[24:25], off offset:224
	v_lshrrev_b32_e32 v26, 2, v28
	v_mul_lo_u32 v163, v18, s38
	v_lshlrev_b32_e32 v151, 2, v21
	v_add_u32_e32 v165, 0, v20
	v_and_b32_e32 v25, 16, v28
	v_lshlrev_b32_e32 v27, 2, v28
	v_mul_lo_u32 v164, v18, s39
	v_and_or_b32 v21, v26, 3, v151
	v_add_u32_e32 v26, v165, v163
	s_lshl_b32 s12, s3, 9
	v_and_b32_e32 v24, 31, v28
	v_add_u32_e32 v28, v165, v164
	s_and_b32 s12, s12, 0x200000
	s_lshl_b32 s36, s3, 10
	s_and_b32 s44, s42, 3
	s_and_b32 s36, s36, 0x400000
	s_lshl_b32 s47, s44, 8
	v_mul_u32_u24_e32 v161, 0x140, v21
	v_mul_u32_u24_e32 v166, 0x110, v24
	s_lshl_b32 s45, s45, 1
	s_or_b32 s44, s46, 15
	s_sub_i32 s45, 63, s45
	v_mov_b32_e32 v167, 0xff800000
	v_mov_b32_e32 v160, 0
	s_mov_b32 s46, 0
	s_waitcnt vmcnt(0)
	ds_write_b128 v26, v[2:5]
	ds_write_b128 v28, v[6:9] offset:17408
	ds_write_b128 v26, v[10:13] offset:8704
	ds_write_b128 v28, v[14:17] offset:27648
	v_and_or_b32 v2, v27, 12, v25
	v_lshlrev_b32_e32 v162, 1, v2
	v_lshlrev_b64 v[2:3], 9, v[22:23]
	v_lshl_add_u64 v[2:3], v[2:3], 0, s[12:13]
	v_lshl_add_u64 v[152:153], v[2:3], 0, s[14:15]
	v_lshlrev_b64 v[2:3], 10, v[18:19]
	v_lshl_add_u64 v[154:155], s[36:37], 0, v[2:3]
	v_mov_b32_e32 v16, v147
	v_mov_b32_e32 v17, v147
	v_or3_b32 v154, v154, s47, v20
	v_mov_b32_e32 v2, v147
	v_mov_b32_e32 v3, v147
	v_mov_b32_e32 v4, v147
	v_mov_b32_e32 v5, v147
	v_mov_b32_e32 v6, v147
	v_mov_b32_e32 v7, v147
	v_mov_b32_e32 v8, v147
	v_mov_b32_e32 v9, v147
	v_mov_b32_e32 v10, v147
	v_mov_b32_e32 v11, v147
	v_mov_b32_e32 v12, v147
	v_mov_b32_e32 v13, v147
	v_mov_b32_e32 v14, v147
	v_mov_b32_e32 v15, v147
	v_mov_b64_e32 v[32:33], v[16:17]
	v_mov_b64_e32 v[48:49], v[16:17]
	v_mov_b64_e32 v[64:65], v[16:17]
	s_mov_b32 s12, 0
	v_mov_b64_e32 v[30:31], v[14:15]
	v_mov_b64_e32 v[28:29], v[12:13]
	v_mov_b64_e32 v[26:27], v[10:11]
	v_mov_b64_e32 v[24:25], v[8:9]
	v_mov_b64_e32 v[22:23], v[6:7]
	v_mov_b64_e32 v[20:21], v[4:5]
	v_mov_b64_e32 v[18:19], v[2:3]
	v_mov_b64_e32 v[46:47], v[14:15]
	v_mov_b64_e32 v[44:45], v[12:13]
	v_mov_b64_e32 v[42:43], v[10:11]
	v_mov_b64_e32 v[40:41], v[8:9]
	v_mov_b64_e32 v[38:39], v[6:7]
	v_mov_b64_e32 v[36:37], v[4:5]
	v_mov_b64_e32 v[34:35], v[2:3]
	v_mov_b64_e32 v[62:63], v[14:15]
	v_mov_b64_e32 v[60:61], v[12:13]
	v_mov_b64_e32 v[58:59], v[10:11]
	v_mov_b64_e32 v[56:57], v[8:9]
	v_mov_b64_e32 v[54:55], v[6:7]
	v_mov_b64_e32 v[52:53], v[4:5]
	v_mov_b64_e32 v[50:51], v[2:3]
	v_lshl_add_u64 v[66:67], s[34:35], 0, v[154:155]
	v_add_co_u32_e32 v68, vcc, 0x35556000, v66
	s_nop 1
	v_addc_co_u32_e32 v69, vcc, 0, v67, vcc
	global_load_dwordx4 v[130:133], v[68:69], off offset:512
	v_add_co_u32_e32 v68, vcc, 0x35d96000, v66
	s_nop 1
	v_addc_co_u32_e32 v69, vcc, 0, v67, vcc
	global_load_dwordx4 v[134:137], v[68:69], off offset:512
	v_add_co_u32_e32 v68, vcc, 0x3555e000, v66
	s_nop 1
	v_addc_co_u32_e32 v69, vcc, 0, v67, vcc
	global_load_dwordx4 v[138:141], v[68:69], off offset:512
	v_add_co_u32_e32 v68, vcc, 0x35d9e000, v66
	s_nop 1
	v_addc_co_u32_e32 v69, vcc, 0, v67, vcc
	global_load_dwordx4 v[142:145], v[68:69], off offset:512
	s_waitcnt lgkmcnt(0)
	s_barrier
	s_cmp_eq_u32 s98, 0
	s_cbranch_scc1 .Lstg_a
	s_barrier
; #define PG8_LAS __attribute__((address_space(3)))
; __device__ __forceinline__ float xhalf_max(float x) { const auto sw = __builtin_amdgcn_permlane32_swap(__float_as_uint(x), __float_as_uint(x), false, false); return fmaxf(__uint_as_float(sw[0]), __uint_as_float(sw[1])); }
; __device__ __forceinline__ void attn_dense_unit(const Params& p, PG8_LAS unsigned char* lds, int b, int n, int qb) {
;     ...
;     for (int t = 0; t < ntile; ++t) {
;         const bool more = (t + 1 < ntile);
;         if (more) A_GLOAD(t + 1);
;         const unsigned long long mw_next = more ? BM[qrow * 64 + t + 1] : 0ull;
;         const int buf = t & 1;
;         if (t * 64 <= qmax_w) {
;             PG8_LAS unsigned char* kb = lds + buf * A_STAGE; PG8_LAS unsigned char* vb = kb + A_KBYTES;
;             f32x16 s0, s1;
; #pragma unroll
;             for (int i = 0; i < 16; ++i) { s0[i] = 0.f; s1[i] = 0.f; }
; #pragma unroll
;             for (int ks = 0; ks < 8; ++ks) {
;                 const bf16x8 k0 = *(const PG8_LAS bf16x8*)(kb + r * A_KP + (ks * 16 + kh * 8) * 2);
;                 const bf16x8 k1 = *(const PG8_LAS bf16x8*)(kb + (32 + r) * A_KP + (ks * 16 + kh * 8) * 2);
;                 s0 = __builtin_amdgcn_mfma_f32_32x32x16_bf16(k0, qf[ks], s0, 0, 0, 0);
;                 s1 = __builtin_amdgcn_mfma_f32_32x32x16_bf16(k1, qf[ks], s1, 0, 0, 0);
;             }
;             const unsigned lo = (unsigned)mw >> (4 * kh), hi = (unsigned)(mw >> 32) >> (4 * kh);
;             float mx = -INFINITY;
; #pragma unroll
;             for (int i = 0; i < 16; ++i) {
;                 const unsigned bit = 1u << ((i & 3) + 8 * (i >> 2));
;                 s0[i] = (lo & bit) ? s0[i] * A_SC : -INFINITY; s1[i] = (hi & bit) ? s1[i] * A_SC : -INFINITY;
;                 mx = fmaxf(mx, fmaxf(s0[i], s1[i]));
;             }
;             mx = xhalf_max(mx);
;             const float m_new = fmaxf(m, mx), m_safe = (m_new == -INFINITY) ? 0.f : m_new;
;             const float alpha = __builtin_amdgcn_exp2f(m - m_safe);
;             float lsum = 0.f;
; #pragma unroll
;             for (int i = 0; i < 16; ++i) { s0[i] = __builtin_amdgcn_exp2f(s0[i] - m_safe); s1[i] = __builtin_amdgcn_exp2f(s1[i] - m_safe); lsum += s0[i] + s1[i]; }
;             l = l * alpha + lsum; m = m_new;
.Lstg_a:
.LBB0_2874:
	s_and_b32 s47, s46, 1
	s_cmp_gt_i32 s12, s44
	s_cselect_b64 s[36:37], -1, 0
	v_lshl_add_u64 v[66:67], s[34:35], 0, v[152:153]
	global_load_dwordx2 v[156:157], v[66:67], off
	s_and_b64 vcc, exec, s[36:37]
	s_cbranch_vccnz .LBB0_2878
	s_mul_i32 s48, s47, 0x9400
	v_add3_u32 v232, s48, v166, v146
	ds_read_b128 v[168:171], v232
	ds_read_b128 v[172:175], v232 offset:8704
	ds_read_b128 v[176:179], v232 offset:32
	ds_read_b128 v[180:183], v232 offset:8736
	ds_read_b128 v[184:187], v232 offset:64
	ds_read_b128 v[188:191], v232 offset:8768
	ds_read_b128 v[192:195], v232 offset:96
	ds_read_b128 v[196:199], v232 offset:8800
	ds_read_b128 v[200:203], v232 offset:128
	ds_read_b128 v[204:207], v232 offset:8832
	ds_read_b128 v[208:211], v232 offset:160
	ds_read_b128 v[212:215], v232 offset:8864
	v_lshrrev_b32_e32 v158, v151, v158
	v_lshrrev_b32_e32 v159, v151, v159
	v_add3_u32 v233, s48, v161, v162
	s_waitcnt lgkmcnt(11)
	v_mfma_f32_32x32x16_bf16 v[66:81], v[168:171], v[126:129], 0
	s_waitcnt lgkmcnt(10)
	v_mfma_f32_32x32x16_bf16 v[82:97], v[172:175], v[126:129], 0
	ds_read_b128 v[216:219], v232 offset:192
	ds_read_b128 v[220:223], v232 offset:8896
	ds_read_b128 v[224:227], v232 offset:224
	ds_read_b128 v[228:231], v232 offset:8928
	s_waitcnt lgkmcnt(13)
	v_mfma_f32_32x32x16_bf16 v[66:81], v[176:179], v[122:125], v[66:81]
	s_waitcnt lgkmcnt(12)
	v_mfma_f32_32x32x16_bf16 v[82:97], v[180:183], v[122:125], v[82:97]
	s_waitcnt lgkmcnt(11)
	v_mfma_f32_32x32x16_bf16 v[66:81], v[184:187], v[118:121], v[66:81]
	s_waitcnt lgkmcnt(10)
	v_mfma_f32_32x32x16_bf16 v[82:97], v[188:191], v[118:121], v[82:97]
	s_waitcnt lgkmcnt(9)
	v_mfma_f32_32x32x16_bf16 v[66:81], v[192:195], v[114:117], v[66:81]
	s_waitcnt lgkmcnt(8)
	v_mfma_f32_32x32x16_bf16 v[82:97], v[196:199], v[114:117], v[82:97]
	s_waitcnt lgkmcnt(7)
	v_mfma_f32_32x32x16_bf16 v[66:81], v[200:203], v[106:109], v[66:81]
	s_waitcnt lgkmcnt(6)
	v_mfma_f32_32x32x16_bf16 v[82:97], v[204:207], v[106:109], v[82:97]
	s_waitcnt lgkmcnt(5)
	v_mfma_f32_32x32x16_bf16 v[66:81], v[208:211], v[102:105], v[66:81]
	s_waitcnt lgkmcnt(4)
	v_mfma_f32_32x32x16_bf16 v[82:97], v[212:215], v[102:105], v[82:97]
	s_waitcnt lgkmcnt(3)
	v_mfma_f32_32x32x16_bf16 v[66:81], v[216:219], v[110:113], v[66:81]
	s_waitcnt lgkmcnt(2)
	v_mfma_f32_32x32x16_bf16 v[82:97], v[220:223], v[110:113], v[82:97]
	s_waitcnt lgkmcnt(1)
	v_mfma_f32_32x32x16_bf16 v[66:81], v[224:227], v[98:101], v[66:81]
	s_waitcnt lgkmcnt(0)
	v_mfma_f32_32x32x16_bf16 v[82:97], v[228:231], v[98:101], v[82:97]
	ds_read_b64_tr_b16 v[168:169], v233 offset:17408
	ds_read_b64_tr_b16 v[170:171], v233 offset:19968
	ds_read_b64_tr_b16 v[172:173], v233 offset:17472
	ds_read_b64_tr_b16 v[174:175], v233 offset:20032
	ds_read_b64_tr_b16 v[176:177], v233 offset:17536
	ds_read_b64_tr_b16 v[178:179], v233 offset:20096
	ds_read_b64_tr_b16 v[180:181], v233 offset:17600
	ds_read_b64_tr_b16 v[182:183], v233 offset:20160
	v_bfe_i32 v234, v158, 0, 1
	v_bfe_i32 v235, v159, 0, 1
	s_nop 1
	v_bfi_b32 v66, v234, v66, s40
	v_bfe_i32 v234, v158, 1, 1
	v_bfi_b32 v82, v235, v82, s40
	v_bfe_i32 v235, v159, 1, 1
	v_bfi_b32 v67, v234, v67, s40
	v_bfe_i32 v234, v158, 2, 1
	v_bfi_b32 v83, v235, v83, s40
	v_bfe_i32 v235, v159, 2, 1
	v_max_f32_e32 v232, v66, v82
	v_max3_f32 v232, v232, v67, v83
	v_bfi_b32 v68, v234, v68, s40
	v_bfe_i32 v234, v158, 3, 1
	v_bfi_b32 v84, v235, v84, s40
	v_bfe_i32 v235, v159, 3, 1
	v_max3_f32 v232, v232, v68, v84
	v_bfi_b32 v69, v234, v69, s40
	v_bfe_i32 v234, v158, 8, 1
	v_bfi_b32 v85, v235, v85, s40
	v_bfe_i32 v235, v159, 8, 1
	v_max3_f32 v232, v232, v69, v85
	ds_read_b64_tr_b16 v[184:185], v233 offset:22528
	ds_read_b64_tr_b16 v[186:187], v233 offset:25088
	ds_read_b64_tr_b16 v[188:189], v233 offset:22592
	ds_read_b64_tr_b16 v[190:191], v233 offset:25152
	ds_read_b64_tr_b16 v[192:193], v233 offset:22656
	ds_read_b64_tr_b16 v[194:195], v233 offset:25216
	ds_read_b64_tr_b16 v[196:197], v233 offset:22720
	ds_read_b64_tr_b16 v[198:199], v233 offset:25280
	v_bfi_b32 v70, v234, v70, s40
	v_bfe_i32 v234, v158, 9, 1
	v_bfi_b32 v86, v235, v86, s40
	v_bfe_i32 v235, v159, 9, 1
	v_max3_f32 v232, v232, v70, v86
	v_bfi_b32 v71, v234, v71, s40
	v_bfe_i32 v234, v158, 10, 1
	v_bfi_b32 v87, v235, v87, s40
	v_bfe_i32 v235, v159, 10, 1
	v_max3_f32 v232, v232, v71, v87
	v_bfi_b32 v72, v234, v72, s40
	v_bfe_i32 v234, v158, 11, 1
	v_bfi_b32 v88, v235, v88, s40
	v_bfe_i32 v235, v159, 11, 1
	v_max3_f32 v232, v232, v72, v88
	v_bfi_b32 v73, v234, v73, s40
	v_bfe_i32 v234, v158, 16, 1
	v_bfi_b32 v89, v235, v89, s40
	v_bfe_i32 v235, v159, 16, 1
	v_max3_f32 v232, v232, v73, v89
	ds_read_b64_tr_b16 v[200:201], v233 offset:27648
	ds_read_b64_tr_b16 v[202:203], v233 offset:30208
	ds_read_b64_tr_b16 v[204:205], v233 offset:27712
	ds_read_b64_tr_b16 v[206:207], v233 offset:30272
	ds_read_b64_tr_b16 v[208:209], v233 offset:27776
	ds_read_b64_tr_b16 v[210:211], v233 offset:30336
	ds_read_b64_tr_b16 v[212:213], v233 offset:27840
	ds_read_b64_tr_b16 v[214:215], v233 offset:30400
	v_bfi_b32 v74, v234, v74, s40
	v_bfe_i32 v234, v158, 17, 1
	v_bfi_b32 v90, v235, v90, s40
	v_bfe_i32 v235, v159, 17, 1
	v_max3_f32 v232, v232, v74, v90
	v_bfi_b32 v75, v234, v75, s40
	v_bfe_i32 v234, v158, 18, 1
	v_bfi_b32 v91, v235, v91, s40
	v_bfe_i32 v235, v159, 18, 1
	v_max3_f32 v232, v232, v75, v91
	v_bfi_b32 v76, v234, v76, s40
	v_bfe_i32 v234, v158, 19, 1
	v_bfi_b32 v92, v235, v92, s40
	v_bfe_i32 v235, v159, 19, 1
	v_max3_f32 v232, v232, v76, v92
	v_bfi_b32 v77, v234, v77, s40
	v_bfe_i32 v234, v158, 24, 1
	v_bfi_b32 v93, v235, v93, s40
	v_bfe_i32 v235, v159, 24, 1
	v_max3_f32 v232, v232, v77, v93
	ds_read_b64_tr_b16 v[216:217], v233 offset:32768
	ds_read_b64_tr_b16 v[218:219], v233 offset:35328
	ds_read_b64_tr_b16 v[220:221], v233 offset:32832
	ds_read_b64_tr_b16 v[222:223], v233 offset:35392
	ds_read_b64_tr_b16 v[224:225], v233 offset:32896
	ds_read_b64_tr_b16 v[226:227], v233 offset:35456
	ds_read_b64_tr_b16 v[228:229], v233 offset:32960
	ds_read_b64_tr_b16 v[230:231], v233 offset:35520
	v_bfi_b32 v78, v234, v78, s40
	v_bfe_i32 v234, v158, 25, 1
	v_bfi_b32 v94, v235, v94, s40
	v_bfe_i32 v235, v159, 25, 1
	v_max3_f32 v232, v232, v78, v94
	v_bfi_b32 v79, v234, v79, s40
	v_bfe_i32 v234, v158, 26, 1
	v_bfi_b32 v95, v235, v95, s40
	v_bfe_i32 v235, v159, 26, 1
	v_max3_f32 v232, v232, v79, v95
	v_bfi_b32 v80, v234, v80, s40
	v_bfe_i32 v234, v158, 27, 1
	v_bfi_b32 v96, v235, v96, s40
	v_bfe_i32 v235, v159, 27, 1
	v_max3_f32 v232, v232, v80, v96
	v_bfi_b32 v81, v234, v81, s40
	v_bfi_b32 v97, v235, v97, s40
	v_max3_f32 v232, v232, v81, v97
	v_mul_f32_e32 v232, 0x3e0293ee, v232
	v_mov_b32_e32 v158, v232
	s_nop 1
	v_permlane32_swap_b32_e32 v232, v158
	v_max3_f32 v158, v167, v232, v158
	v_cmp_neq_f32_e32 vcc, s40, v158
	s_nop 1
	v_cndmask_b32_e32 v236, 0, v158, vcc
	v_sub_f32_e32 v234, v167, v236
	v_exp_f32_e32 v234, v234
	v_mul_f32_e32 v236, -1.0, v236
	s_cmp_eq_u32 s98, 0
	s_cbranch_scc1 .Lattn_nr_x1
; #define A_GLOAD(t) do { _Pragma("unroll") for (int _i = 0; _i < 2; ++_i) { kst[_i] = *(const u32x4*)(kg + (size_t)((t) * 64 + _i * 32) * 512); vst[_i] = *(const u32x4*)(vg + (size_t)((t) * 64 + _i * 32) * 512); } } while (0)
; #define A_LSTORE(buf) do { _Pragma("unroll") for (int _i = 0; _i < 2; ++_i) { *(PG8_LAS u32x4*)(lds + (buf) * A_STAGE + (srow + _i * 32) * A_KP + sch * 16) = kst[_i]; \
;         *(PG8_LAS u32x4*)(lds + (buf) * A_STAGE + A_KBYTES + (srow + _i * 32) * A_VP + sch * 16) = vst[_i]; } } while (0)
; __device__ __forceinline__ void attn_dense_unit(const Params& p, PG8_LAS unsigned char* lds, int b, int n, int qb) {
;     ...
;     A_GLOAD(0); A_LSTORE(0);
;     unsigned long long mw = BM[qrow * 64];
;     __syncthreads();
;     const int i16 = lane & 15, g2 = (lane >> 4) & 1;
;     const int vlane_off = (4 * kh + (i16 >> 2)) * A_VP + (16 * g2 + 4 * (i16 & 3)) * 2;
;     for (int t = 0; t < ntile; ++t) {
;         const bool more = (t + 1 < ntile);
;         if (more) A_GLOAD(t + 1);
	s_xor_b32 s49, s47, 1
	s_mul_i32 s49, s49, 0x9400
	v_add_u32_e32 v244, s49, v165
	v_add_u32_e32 v245, v244, v163
	v_add_u32_e32 v244, v244, v164
	s_waitcnt vmcnt(4)
	ds_write_b128 v245, v[130:133]
	s_waitcnt vmcnt(3)
	ds_write_b128 v244, v[134:137] offset:17408
	s_waitcnt vmcnt(2)
	ds_write_b128 v245, v[138:141] offset:8704
	s_waitcnt vmcnt(1)
	ds_write_b128 v244, v[142:145] offset:27648
	s_add_i32 s48, s46, 1
	s_cmp_lt_i32 s48, s45
	s_cbranch_scc0 .Lattn_nr_ldy
	v_lshl_add_u64 v[240:241], s[34:35], 0, v[154:155]
	v_add_co_u32_e32 v242, vcc, 0x35566000, v240
	s_nop 1
	v_addc_co_u32_e32 v243, vcc, 0, v241, vcc
	global_load_dwordx4 v[130:133], v[242:243], off offset:512
	v_add_co_u32_e32 v242, vcc, 0x35da6000, v240
	s_nop 1
	v_addc_co_u32_e32 v243, vcc, 0, v241, vcc
	global_load_dwordx4 v[134:137], v[242:243], off offset:512
	v_add_co_u32_e32 v242, vcc, 0x3556e000, v240
	s_nop 1
	v_addc_co_u32_e32 v243, vcc, 0, v241, vcc
	global_load_dwordx4 v[138:141], v[242:243], off offset:512
	v_add_co_u32_e32 v242, vcc, 0x35dae000, v240
	s_nop 1
	v_addc_co_u32_e32 v243, vcc, 0, v241, vcc
	global_load_dwordx4 v[142:145], v[242:243], off offset:512

; #define A_LSTORE(buf) do { _Pragma("unroll") for (int _i = 0; _i < 2; ++_i) { *(PG8_LAS u32x4*)(lds + (buf) * A_STAGE + (srow + _i * 32) * A_KP + sch * 16) = kst[_i]; \
;         *(PG8_LAS u32x4*)(lds + (buf) * A_STAGE + A_KBYTES + (srow + _i * 32) * A_VP + sch * 16) = vst[_i]; } } while (0)
; __device__ __forceinline__ void attn_dense_unit(const Params& p, PG8_LAS unsigned char* lds, int b, int n, int qb) {
;     ...
;             const float alpha = __builtin_amdgcn_exp2f(m - m_safe);
;             float lsum = 0.f;
; #pragma unroll
;             for (int i = 0; i < 16; ++i) { s0[i] = __builtin_amdgcn_exp2f(s0[i] - m_safe); s1[i] = __builtin_amdgcn_exp2f(s1[i] - m_safe); lsum += s0[i] + s1[i]; }
;             l = l * alpha + lsum; m = m_new;
;             if (__ballot(alpha != 1.0f) != 0ull) {
; #pragma unroll
;                 for (int dt = 0; dt < 4; ++dt)
; #pragma unroll
;                     for (int i = 0; i < 16; ++i) O[dt][i] *= alpha;
;             }
;             if (more) A_LSTORE(buf ^ 1);
.Lattn_nr_x1:
	s_barrier
	v_fmamk_f32 v66, v66, 0x3e0293ee, v236
	v_fmamk_f32 v82, v82, 0x3e0293ee, v236
	v_cmp_neq_f32_e32 vcc, 1.0, v234
	s_cbranch_vccz .Lattn_nr
	v_pk_mul_f32 v[64:65], v[64:65], v[234:235] op_sel_hi:[1,0]
	v_pk_mul_f32 v[62:63], v[62:63], v[234:235] op_sel_hi:[1,0]
	v_pk_mul_f32 v[60:61], v[60:61], v[234:235] op_sel_hi:[1,0]
	v_pk_mul_f32 v[58:59], v[58:59], v[234:235] op_sel_hi:[1,0]
	v_pk_mul_f32 v[56:57], v[56:57], v[234:235] op_sel_hi:[1,0]
	v_pk_mul_f32 v[54:55], v[54:55], v[234:235] op_sel_hi:[1,0]
	v_pk_mul_f32 v[52:53], v[52:53], v[234:235] op_sel_hi:[1,0]
	v_pk_mul_f32 v[50:51], v[50:51], v[234:235] op_sel_hi:[1,0]
	v_pk_mul_f32 v[48:49], v[48:49], v[234:235] op_sel_hi:[1,0]
	v_pk_mul_f32 v[46:47], v[46:47], v[234:235] op_sel_hi:[1,0]
	v_pk_mul_f32 v[44:45], v[44:45], v[234:235] op_sel_hi:[1,0]
	v_pk_mul_f32 v[42:43], v[42:43], v[234:235] op_sel_hi:[1,0]
	v_pk_mul_f32 v[40:41], v[40:41], v[234:235] op_sel_hi:[1,0]
	v_pk_mul_f32 v[38:39], v[38:39], v[234:235] op_sel_hi:[1,0]
	v_pk_mul_f32 v[36:37], v[36:37], v[234:235] op_sel_hi:[1,0]
	v_pk_mul_f32 v[34:35], v[34:35], v[234:235] op_sel_hi:[1,0]
	v_pk_mul_f32 v[32:33], v[32:33], v[234:235] op_sel_hi:[1,0]
	v_pk_mul_f32 v[30:31], v[30:31], v[234:235] op_sel_hi:[1,0]
	v_pk_mul_f32 v[28:29], v[28:29], v[234:235] op_sel_hi:[1,0]
	v_pk_mul_f32 v[26:27], v[26:27], v[234:235] op_sel_hi:[1,0]
	v_pk_mul_f32 v[24:25], v[24:25], v[234:235] op_sel_hi:[1,0]
	v_pk_mul_f32 v[22:23], v[22:23], v[234:235] op_sel_hi:[1,0]
	v_pk_mul_f32 v[20:21], v[20:21], v[234:235] op_sel_hi:[1,0]
	v_pk_mul_f32 v[18:19], v[18:19], v[234:235] op_sel_hi:[1,0]
	v_pk_mul_f32 v[16:17], v[16:17], v[234:235] op_sel_hi:[1,0]
	v_pk_mul_f32 v[14:15], v[14:15], v[234:235] op_sel_hi:[1,0]
	v_pk_mul_f32 v[12:13], v[12:13], v[234:235] op_sel_hi:[1,0]
	v_pk_mul_f32 v[10:11], v[10:11], v[234:235] op_sel_hi:[1,0]
	v_pk_mul_f32 v[8:9], v[8:9], v[234:235] op_sel_hi:[1,0]
	v_pk_mul_f32 v[6:7], v[6:7], v[234:235] op_sel_hi:[1,0]
	v_pk_mul_f32 v[4:5], v[4:5], v[234:235] op_sel_hi:[1,0]
	v_pk_mul_f32 v[2:3], v[2:3], v[234:235] op_sel_hi:[1,0]
.Lattn_nr:
	v_fmamk_f32 v67, v67, 0x3e0293ee, v236
	v_exp_f32_e32 v66, v66
	v_fmamk_f32 v83, v83, 0x3e0293ee, v236
	v_exp_f32_e32 v82, v82
	v_fmamk_f32 v68, v68, 0x3e0293ee, v236
	v_exp_f32_e32 v67, v67
	v_fmamk_f32 v84, v84, 0x3e0293ee, v236
	v_exp_f32_e32 v83, v83
	v_fmamk_f32 v69, v69, 0x3e0293ee, v236
	v_exp_f32_e32 v68, v68
	v_fmamk_f32 v85, v85, 0x3e0293ee, v236
	v_exp_f32_e32 v84, v84
	v_fmamk_f32 v70, v70, 0x3e0293ee, v236
	v_exp_f32_e32 v69, v69
	v_fmamk_f32 v86, v86, 0x3e0293ee, v236
	v_exp_f32_e32 v85, v85
	v_fmamk_f32 v71, v71, 0x3e0293ee, v236
	v_exp_f32_e32 v70, v70
	v_fmamk_f32 v87, v87, 0x3e0293ee, v236
	v_exp_f32_e32 v86, v86
	v_fmamk_f32 v72, v72, 0x3e0293ee, v236
	v_exp_f32_e32 v71, v71
	v_fmamk_f32 v88, v88, 0x3e0293ee, v236
	v_exp_f32_e32 v87, v87
	v_fmamk_f32 v73, v73, 0x3e0293ee, v236
	v_exp_f32_e32 v72, v72
	v_fmamk_f32 v89, v89, 0x3e0293ee, v236
	v_exp_f32_e32 v88, v88
	v_fmamk_f32 v74, v74, 0x3e0293ee, v236
	v_exp_f32_e32 v73, v73
	v_fmamk_f32 v90, v90, 0x3e0293ee, v236
	v_exp_f32_e32 v89, v89
	v_fmamk_f32 v75, v75, 0x3e0293ee, v236
	v_exp_f32_e32 v74, v74
	v_fmamk_f32 v91, v91, 0x3e0293ee, v236
	v_exp_f32_e32 v90, v90
	v_fmamk_f32 v76, v76, 0x3e0293ee, v236
	v_exp_f32_e32 v75, v75
	v_fmamk_f32 v92, v92, 0x3e0293ee, v236
	v_exp_f32_e32 v91, v91
	v_fmamk_f32 v77, v77, 0x3e0293ee, v236
	v_exp_f32_e32 v76, v76
	v_fmamk_f32 v93, v93, 0x3e0293ee, v236
	v_exp_f32_e32 v92, v92
	v_fmamk_f32 v78, v78, 0x3e0293ee, v236
	v_exp_f32_e32 v77, v77
	v_fmamk_f32 v94, v94, 0x3e0293ee, v236
	v_exp_f32_e32 v93, v93
	v_fmamk_f32 v79, v79, 0x3e0293ee, v236
	v_exp_f32_e32 v78, v78
	v_fmamk_f32 v95, v95, 0x3e0293ee, v236
	v_exp_f32_e32 v94, v94
	v_fmamk_f32 v80, v80, 0x3e0293ee, v236
	v_exp_f32_e32 v79, v79
	v_fmamk_f32 v96, v96, 0x3e0293ee, v236
	v_exp_f32_e32 v95, v95
	v_fmamk_f32 v81, v81, 0x3e0293ee, v236
	v_exp_f32_e32 v80, v80
	v_fmamk_f32 v97, v97, 0x3e0293ee, v236
	v_exp_f32_e32 v96, v96
	v_exp_f32_e32 v81, v81
	v_exp_f32_e32 v97, v97
	s_cmp_lg_u32 s98, 0
	s_cbranch_scc1 .Lattn_nr_y2
	s_xor_b32 s49, s47, 1
	s_mul_i32 s49, s49, 0x9400
	v_add_u32_e32 v232, s49, v165
	v_add_u32_e32 v235, v232, v163
	v_add_u32_e32 v232, v232, v164
	s_waitcnt vmcnt(4)
	ds_write_b128 v235, v[130:133]
	s_waitcnt vmcnt(3)
	ds_write_b128 v232, v[134:137] offset:17408
	s_waitcnt vmcnt(2)
	ds_write_b128 v235, v[138:141] offset:8704
	s_waitcnt vmcnt(1)
	ds_write_b128 v232, v[142:145] offset:27648
	s_add_i32 s48, s46, 1
	s_cmp_lt_i32 s48, s45
	s_cbranch_scc0 .Lattn_nr_ld
	v_lshl_add_u64 v[232:233], s[34:35], 0, v[154:155]
	v_add_co_u32_e32 v236, vcc, 0x35566000, v232
	s_nop 1
	v_addc_co_u32_e32 v237, vcc, 0, v233, vcc
	global_load_dwordx4 v[130:133], v[236:237], off offset:512
	v_add_co_u32_e32 v236, vcc, 0x35da6000, v232
	s_nop 1
	v_addc_co_u32_e32 v237, vcc, 0, v233, vcc
	global_load_dwordx4 v[134:137], v[236:237], off offset:512
	v_add_co_u32_e32 v236, vcc, 0x3556e000, v232
	s_nop 1
	v_addc_co_u32_e32 v237, vcc, 0, v233, vcc
	global_load_dwordx4 v[138:141], v[236:237], off offset:512
	v_add_co_u32_e32 v236, vcc, 0x35dae000, v232
	s_nop 1
	v_addc_co_u32_e32 v237, vcc, 0, v233, vcc
	global_load_dwordx4 v[142:145], v[236:237], off offset:512
; #define PG8_LAS __attribute__((address_space(3)))
; __device__ __forceinline__ unsigned cvt_pk_bf16(float lo, float hi) { unsigned r; asm volatile("v_cvt_pk_bf16_f32 %0, %1, %2" : "=v"(r) : "v"(lo), "v"(hi)); return r; }
; __device__ __forceinline__ unsigned cvt_pk_bf16(float lo, float hi) { unsigned r; asm volatile("v_cvt_pk_bf16_f32 %0, %1, %2" : "=v"(r) : "v"(lo), "v"(hi)); return r; }
; #define A_LSTORE(buf) do { _Pragma("unroll") for (int _i = 0; _i < 2; ++_i) { *(PG8_LAS u32x4*)(lds + (buf) * A_STAGE + (srow + _i * 32) * A_KP + sch * 16) = kst[_i]; \
;         *(PG8_LAS u32x4*)(lds + (buf) * A_STAGE + A_KBYTES + (srow + _i * 32) * A_VP + sch * 16) = vst[_i]; } } while (0)
; __device__ __forceinline__ void attn_dense_unit(const Params& p, PG8_LAS unsigned char* lds, int b, int n, int qb) {
;     ...
;             bf16x8 pf[2][2];
; #pragma unroll
;             for (int sx = 0; sx < 2; ++sx) {
;                 u32x4 w0, w1;
;                 w0.x = cvt_pk_bf16(s0[8 * sx], s0[8 * sx + 1]); w0.y = cvt_pk_bf16(s0[8 * sx + 2], s0[8 * sx + 3]); w0.z = cvt_pk_bf16(s0[8 * sx + 4], s0[8 * sx + 5]); w0.w = cvt_pk_bf16(s0[8 * sx + 6], s0[8 * sx + 7]);
;                 w1.x = cvt_pk_bf16(s1[8 * sx], s1[8 * sx + 1]); w1.y = cvt_pk_bf16(s1[8 * sx + 2], s1[8 * sx + 3]); w1.z = cvt_pk_bf16(s1[8 * sx + 4], s1[8 * sx + 5]); w1.w = cvt_pk_bf16(s1[8 * sx + 6], s1[8 * sx + 7]);
;                 pf[0][sx] = __builtin_bit_cast(bf16x8, w0); pf[1][sx] = __builtin_bit_cast(bf16x8, w1);
;             }
; #pragma unroll
;             for (int st = 0; st < 2; ++st)
; #pragma unroll
;                 for (int sx = 0; sx < 2; ++sx)
; #pragma unroll
;                     for (int dt = 0; dt < 4; ++dt) {
;                         PG8_LAS unsigned char* a = vb + vlane_off + (st * 32 + 16 * sx) * A_VP + dt * 64;
;                         const s16x4 vlo = __builtin_amdgcn_ds_read_tr16_b64_v4i16((PG8_LAS s16x4*)a);
;                         const s16x4 vhi = __builtin_amdgcn_ds_read_tr16_b64_v4i16((PG8_LAS s16x4*)(a + 8 * A_VP));
;                         const bf16x8 vf = __builtin_shufflevector(vlo, vhi, 0, 1, 2, 3, 4, 5, 6, 7);
;                         O[dt] = __builtin_amdgcn_mfma_f32_32x32x16_bf16(vf, pf[st][sx], O[dt], 0, 0, 0);
;                     }
;         }
;         if (more && !(t * 64 <= qmax_w)) A_LSTORE(buf ^ 1);
;         __syncthreads();
;         mw = mw_next;
;     }
.Lattn_nr_ld:
.Lattn_nr_y2:
	v_cvt_pk_bf16_f32 v240, v66, v67
	v_cvt_pk_bf16_f32 v241, v68, v69
	v_cvt_pk_bf16_f32 v242, v70, v71
	v_cvt_pk_bf16_f32 v243, v72, v73
	v_cvt_pk_bf16_f32 v244, v74, v75
	v_cvt_pk_bf16_f32 v245, v76, v77
	v_cvt_pk_bf16_f32 v246, v78, v79
	v_cvt_pk_bf16_f32 v247, v80, v81
	v_cvt_pk_bf16_f32 v248, v82, v83
	v_cvt_pk_bf16_f32 v249, v84, v85
	v_cvt_pk_bf16_f32 v250, v86, v87
	v_cvt_pk_bf16_f32 v251, v88, v89
	v_cvt_pk_bf16_f32 v252, v90, v91
	v_cvt_pk_bf16_f32 v253, v92, v93
	v_cvt_pk_bf16_f32 v254, v94, v95
	v_cvt_pk_bf16_f32 v255, v96, v97
	s_waitcnt lgkmcnt(0)
	v_mfma_f32_32x32x16_bf16 v[50:65], v[168:171], v[240:243], v[50:65]
	v_add_f32_e32 v159, v67, v83
	v_add_f32_e32 v235, v66, v82
	v_mfma_f32_32x32x16_bf16 v[34:49], v[172:175], v[240:243], v[34:49]
	v_add_f32_e32 v159, v159, v235
	v_add_f32_e32 v235, v68, v84
	v_mfma_f32_32x32x16_bf16 v[18:33], v[176:179], v[240:243], v[18:33]
	v_add_f32_e32 v159, v235, v159
	v_add_f32_e32 v235, v69, v85
	v_mfma_f32_32x32x16_bf16 v[2:17], v[180:183], v[240:243], v[2:17]
	v_add_f32_e32 v159, v235, v159
	v_add_f32_e32 v235, v70, v86
	v_mfma_f32_32x32x16_bf16 v[50:65], v[184:187], v[244:247], v[50:65]
	v_add_f32_e32 v159, v235, v159
	v_add_f32_e32 v235, v71, v87
	v_mfma_f32_32x32x16_bf16 v[34:49], v[188:191], v[244:247], v[34:49]
	v_add_f32_e32 v159, v235, v159
	v_add_f32_e32 v235, v72, v88
	v_mfma_f32_32x32x16_bf16 v[18:33], v[192:195], v[244:247], v[18:33]
	v_add_f32_e32 v159, v235, v159
	v_add_f32_e32 v235, v73, v89
	v_mfma_f32_32x32x16_bf16 v[2:17], v[196:199], v[244:247], v[2:17]
	v_add_f32_e32 v159, v235, v159
	v_add_f32_e32 v235, v74, v90
	v_mfma_f32_32x32x16_bf16 v[50:65], v[200:203], v[248:251], v[50:65]
	v_add_f32_e32 v159, v235, v159
	v_add_f32_e32 v235, v75, v91
	v_mfma_f32_32x32x16_bf16 v[34:49], v[204:207], v[248:251], v[34:49]
	v_add_f32_e32 v159, v235, v159
	v_add_f32_e32 v235, v76, v92
	v_mfma_f32_32x32x16_bf16 v[18:33], v[208:211], v[248:251], v[18:33]
	v_add_f32_e32 v159, v235, v159
	v_add_f32_e32 v235, v77, v93
	v_mfma_f32_32x32x16_bf16 v[2:17], v[212:215], v[248:251], v[2:17]
	v_add_f32_e32 v159, v235, v159
	v_add_f32_e32 v235, v78, v94
	v_mfma_f32_32x32x16_bf16 v[50:65], v[216:219], v[252:255], v[50:65]
	v_add_f32_e32 v159, v235, v159
	v_add_f32_e32 v235, v79, v95
	v_mfma_f32_32x32x16_bf16 v[34:49], v[220:223], v[252:255], v[34:49]
	v_add_f32_e32 v159, v235, v159
	v_add_f32_e32 v235, v80, v96
	v_mfma_f32_32x32x16_bf16 v[18:33], v[224:227], v[252:255], v[18:33]
	v_add_f32_e32 v159, v235, v159
	v_add_f32_e32 v235, v81, v97
	v_mfma_f32_32x32x16_bf16 v[2:17], v[228:231], v[252:255], v[2:17]
	v_add_f32_e32 v159, v235, v159
	v_fmac_f32_e32 v159, v160, v234
	v_mov_b32_e32 v160, v159
	s_andn2_b64 vcc, exec, s[36:37]
	s_cbranch_vccz .LBB0_2879
	s_branch .LBB0_2880
.LBB0_2878:
	v_mov_b32_e32 v158, v167
	s_cmp_eq_u32 s98, 0
	s_cbranch_scc1 .Lstg_c1
	s_xor_b32 s36, s47, 1
	s_mul_i32 s36, s36, 0x9400
	v_add_u32_e32 v66, s36, v165
	v_add_u32_e32 v67, v66, v163
	v_add_u32_e32 v66, v66, v164
	s_waitcnt vmcnt(4)
	ds_write_b128 v67, v[130:133]
	s_waitcnt vmcnt(3)
	ds_write_b128 v66, v[134:137] offset:17408
	s_waitcnt vmcnt(2)
	ds_write_b128 v67, v[138:141] offset:8704
	s_waitcnt vmcnt(1)
	ds_write_b128 v66, v[142:145] offset:27648
	s_add_i32 s48, s46, 1
	s_cmp_lt_i32 s48, s45
	s_cbranch_scc0 .Lattn_skip_ldy
	v_lshl_add_u64 v[66:67], s[34:35], 0, v[154:155]
	v_add_co_u32_e32 v68, vcc, 0x35566000, v66
	s_nop 1
	v_addc_co_u32_e32 v69, vcc, 0, v67, vcc
	global_load_dwordx4 v[130:133], v[68:69], off offset:512
	v_add_co_u32_e32 v68, vcc, 0x35da6000, v66
	s_nop 1
	v_addc_co_u32_e32 v69, vcc, 0, v67, vcc
	global_load_dwordx4 v[134:137], v[68:69], off offset:512
	v_add_co_u32_e32 v68, vcc, 0x3556e000, v66
	s_nop 1
	v_addc_co_u32_e32 v69, vcc, 0, v67, vcc
	global_load_dwordx4 v[138:141], v[68:69], off offset:512
	v_add_co_u32_e32 v68, vcc, 0x35dae000, v66
	s_nop 1
	v_addc_co_u32_e32 v69, vcc, 0, v67, vcc
	global_load_dwordx4 v[142:145], v[68:69], off offset:512
.Lattn_skip_ldy:
	s_waitcnt lgkmcnt(0)
	s_barrier
	s_branch .LBB0_2880
.Lstg_c1:
	s_barrier
.LBB0_2879:
	s_xor_b32 s36, s47, 1
	s_mul_i32 s36, s36, 0x9400
	v_add_u32_e32 v66, s36, v165
	v_add_u32_e32 v67, v66, v163
	v_add_u32_e32 v66, v66, v164
	s_waitcnt vmcnt(4)
	ds_write_b128 v67, v[130:133]
	s_waitcnt vmcnt(3)
	ds_write_b128 v66, v[134:137] offset:17408
	s_waitcnt vmcnt(2)
	ds_write_b128 v67, v[138:141] offset:8704
	s_waitcnt vmcnt(1)
	ds_write_b128 v66, v[142:145] offset:27648
	s_add_i32 s48, s46, 1
	s_cmp_lt_i32 s48, s45
	s_cbranch_scc0 .Lattn_skip_ld
	v_lshl_add_u64 v[66:67], s[34:35], 0, v[154:155]
	v_add_co_u32_e32 v68, vcc, 0x35566000, v66
	s_nop 1
	v_addc_co_u32_e32 v69, vcc, 0, v67, vcc
	global_load_dwordx4 v[130:133], v[68:69], off offset:512
	v_add_co_u32_e32 v68, vcc, 0x35da6000, v66
	s_nop 1
	v_addc_co_u32_e32 v69, vcc, 0, v67, vcc
	global_load_dwordx4 v[134:137], v[68:69], off offset:512
	v_add_co_u32_e32 v68, vcc, 0x3556e000, v66
	s_nop 1
	v_addc_co_u32_e32 v69, vcc, 0, v67, vcc
	global_load_dwordx4 v[138:141], v[68:69], off offset:512
	v_add_co_u32_e32 v68, vcc, 0x35dae000, v66
	s_nop 1
	v_addc_co_u32_e32 v69, vcc, 0, v67, vcc
	global_load_dwordx4 v[142:145], v[68:69], off offset:512
.Lattn_skip_ld:
.LBB0_2880:
	s_add_i32 s46, s46, 1
	s_add_i32 s12, s12, 64
	v_lshl_add_u64 v[152:153], v[152:153], 0, 8
	s_cmp_eq_u32 s45, s46
	v_lshl_add_u64 v[154:155], v[154:155], 0, s[16:17]
	s_waitcnt lgkmcnt(0)
	s_barrier
	s_cbranch_scc1 .LBB0_2882
	v_mov_b32_e32 v167, v158
	s_waitcnt vmcnt(4)
	v_mov_b64_e32 v[158:159], v[156:157]
	s_branch .LBB0_2874
.LBB0_2882:
	s_cmp_lg_u32 s98, 0
	s_cbranch_scc1 .Lstg_d
	s_barrier

; __device__ __forceinline__ int fresh_tid() { int t = threadIdx.x; asm volatile("" : "+v"(t)); return t; }
; __device__ __forceinline__ void lru_fixup_unit(const Params& p, int ck) {
;     const int tid = fresh_tid(), ch = tid * 2;
;     unsigned char* ws = p.ws;
;     const bf16_t* GG = (const bf16_t*)(ws + WS_GG);
;     const float* HL = (const float*)(ws + WS_HL); const float* PP = (const float*)(ws + WS_PP); const float* SUMA = (const float*)(ws + WS_SUMA); const float* SUMH = (const float*)(ws + WS_SUMH);
;     bf16_t* CATB = (bf16_t*)(ws + WS_CATB); float* PS = (float*)(ws + WS_PS);
;     typedef float f32x2 __attribute__((ext_vector_type(2)));
;     f32x2 carry = (f32x2){0.f, 0.f};
;     const bool prompt = ck < LRU_PCHUNK;
;     if (prompt) {
;         const int b = ck / LRU_CPB, kk = ck % LRU_CPB;
; #pragma unroll 16
;         for (int j = 0; j < kk; ++j) {
;             const f32x2 A = *(const f32x2*)(SUMA + (size_t)(b * LRU_CPB + j) * DRNN + ch), Hh = *(const f32x2*)(SUMH + (size_t)(b * LRU_CPB + j) * DRNN + ch);
;             carry = A * carry + Hh;
;         }
;     }
.LBB0_2893:
	s_or_b64 exec, exec, s[40:41]
	s_waitcnt lgkmcnt(0)
	s_barrier
	ds_read_b32 v2, v1
	s_mov_b64 s[40:41], -1
	s_waitcnt lgkmcnt(0)
	v_cmp_lt_u32_e32 vcc, s77, v2
	v_readfirstlane_b32 s44, v2
	s_cbranch_vccnz .LBB0_2888
	s_cmpk_gt_u32 s44, 0x7f
	s_cbranch_scc0 .LBB0_2910
	v_mov_b32_e32 v2, v0
	s_add_i32 s40, s44, 0xffffff80
	s_cmpk_gt_u32 s40, 0x7f
	v_lshlrev_b32_e32 v6, 1, v2
	v_mov_b32_e32 v2, 0
	v_mov_b32_e32 v3, 0
	s_cbranch_scc1 .LBB0_2905
	s_and_b32 s16, s44, 63
	s_cmp_eq_u32 s16, 0
	s_cbranch_scc1 .LBB0_2905
	s_and_b32 s41, s44, 64
	s_lshl_b32 s41, s41, 12
	s_add_u32 s78, s8, s41
	s_addc_u32 s79, s9, 0
	s_add_u32 s42, s10, s41
	s_addc_u32 s43, s11, 0
	v_lshlrev_b32_e32 v4, 2, v6
.Lfix_blk:
	global_load_dwordx2 v[128:129], v4, s[78:79]
	global_load_dwordx2 v[130:131], v4, s[42:43]
	s_add_u32 s78, s78, 0x1000
	s_addc_u32 s79, s79, 0
	s_add_u32 s42, s42, 0x1000
	s_addc_u32 s43, s43, 0
	global_load_dwordx2 v[132:133], v4, s[78:79]
	global_load_dwordx2 v[134:135], v4, s[42:43]
	s_add_u32 s78, s78, 0x1000
	s_addc_u32 s79, s79, 0
	s_add_u32 s42, s42, 0x1000
	s_addc_u32 s43, s43, 0
	global_load_dwordx2 v[136:137], v4, s[78:79]
	global_load_dwordx2 v[138:139], v4, s[42:43]
	s_add_u32 s78, s78, 0x1000
	s_addc_u32 s79, s79, 0
	s_add_u32 s42, s42, 0x1000
	s_addc_u32 s43, s43, 0
	global_load_dwordx2 v[140:141], v4, s[78:79]
	global_load_dwordx2 v[142:143], v4, s[42:43]
	s_add_u32 s78, s78, 0x1000
	s_addc_u32 s79, s79, 0
	s_add_u32 s42, s42, 0x1000
	s_addc_u32 s43, s43, 0
	global_load_dwordx2 v[144:145], v4, s[78:79]
	global_load_dwordx2 v[146:147], v4, s[42:43]
	s_add_u32 s78, s78, 0x1000
	s_addc_u32 s79, s79, 0
	s_add_u32 s42, s42, 0x1000
	s_addc_u32 s43, s43, 0
	global_load_dwordx2 v[148:149], v4, s[78:79]
	global_load_dwordx2 v[150:151], v4, s[42:43]
	s_add_u32 s78, s78, 0x1000
	s_addc_u32 s79, s79, 0
	s_add_u32 s42, s42, 0x1000
	s_addc_u32 s43, s43, 0
	global_load_dwordx2 v[152:153], v4, s[78:79]
	global_load_dwordx2 v[154:155], v4, s[42:43]
	s_add_u32 s78, s78, 0x1000
	s_addc_u32 s79, s79, 0
	s_add_u32 s42, s42, 0x1000
	s_addc_u32 s43, s43, 0
	global_load_dwordx2 v[156:157], v4, s[78:79]
	global_load_dwordx2 v[158:159], v4, s[42:43]
	s_add_u32 s78, s78, 0x1000
	s_addc_u32 s79, s79, 0
	s_add_u32 s42, s42, 0x1000
	s_addc_u32 s43, s43, 0
	global_load_dwordx2 v[160:161], v4, s[78:79]
	global_load_dwordx2 v[162:163], v4, s[42:43]
	s_add_u32 s78, s78, 0x1000
	s_addc_u32 s79, s79, 0
	s_add_u32 s42, s42, 0x1000
	s_addc_u32 s43, s43, 0
	global_load_dwordx2 v[164:165], v4, s[78:79]
	global_load_dwordx2 v[166:167], v4, s[42:43]
	s_add_u32 s78, s78, 0x1000
	s_addc_u32 s79, s79, 0
	s_add_u32 s42, s42, 0x1000
	s_addc_u32 s43, s43, 0
	global_load_dwordx2 v[168:169], v4, s[78:79]
	global_load_dwordx2 v[170:171], v4, s[42:43]
	s_add_u32 s78, s78, 0x1000
	s_addc_u32 s79, s79, 0
	s_add_u32 s42, s42, 0x1000
	s_addc_u32 s43, s43, 0
	global_load_dwordx2 v[172:173], v4, s[78:79]
	global_load_dwordx2 v[174:175], v4, s[42:43]
	s_add_u32 s78, s78, 0x1000
	s_addc_u32 s79, s79, 0
	s_add_u32 s42, s42, 0x1000
	s_addc_u32 s43, s43, 0
	global_load_dwordx2 v[176:177], v4, s[78:79]
	global_load_dwordx2 v[178:179], v4, s[42:43]
	s_add_u32 s78, s78, 0x1000
	s_addc_u32 s79, s79, 0
	s_add_u32 s42, s42, 0x1000
	s_addc_u32 s43, s43, 0
	global_load_dwordx2 v[180:181], v4, s[78:79]
	global_load_dwordx2 v[182:183], v4, s[42:43]
	s_add_u32 s78, s78, 0x1000
	s_addc_u32 s79, s79, 0
	s_add_u32 s42, s42, 0x1000
	s_addc_u32 s43, s43, 0
	global_load_dwordx2 v[184:185], v4, s[78:79]
	global_load_dwordx2 v[186:187], v4, s[42:43]
	s_add_u32 s78, s78, 0x1000
	s_addc_u32 s79, s79, 0
	s_add_u32 s42, s42, 0x1000
	s_addc_u32 s43, s43, 0
	global_load_dwordx2 v[188:189], v4, s[78:79]
	global_load_dwordx2 v[190:191], v4, s[42:43]
	s_add_u32 s78, s78, 0x1000
	s_addc_u32 s79, s79, 0
	s_add_u32 s42, s42, 0x1000
	s_addc_u32 s43, s43, 0
	s_waitcnt vmcnt(30)
	v_pk_fma_f32 v[2:3], v[2:3], v[128:129], v[130:131]
	s_cmp_lt_u32 s16, 2
	s_cbranch_scc1 .Lfix_done
	s_waitcnt vmcnt(28)
	v_pk_fma_f32 v[2:3], v[2:3], v[132:133], v[134:135]
	s_cmp_lt_u32 s16, 3
	s_cbranch_scc1 .Lfix_done
	s_waitcnt vmcnt(26)
	v_pk_fma_f32 v[2:3], v[2:3], v[136:137], v[138:139]
	s_cmp_lt_u32 s16, 4
	s_cbranch_scc1 .Lfix_done
	s_waitcnt vmcnt(24)
	v_pk_fma_f32 v[2:3], v[2:3], v[140:141], v[142:143]
	s_cmp_lt_u32 s16, 5
	s_cbranch_scc1 .Lfix_done
	s_waitcnt vmcnt(22)
	v_pk_fma_f32 v[2:3], v[2:3], v[144:145], v[146:147]
	s_cmp_lt_u32 s16, 6
	s_cbranch_scc1 .Lfix_done
	s_waitcnt vmcnt(20)
	v_pk_fma_f32 v[2:3], v[2:3], v[148:149], v[150:151]
	s_cmp_lt_u32 s16, 7
	s_cbranch_scc1 .Lfix_done
	s_waitcnt vmcnt(18)
	v_pk_fma_f32 v[2:3], v[2:3], v[152:153], v[154:155]
	s_cmp_lt_u32 s16, 8
	s_cbranch_scc1 .Lfix_done
	s_waitcnt vmcnt(16)
	v_pk_fma_f32 v[2:3], v[2:3], v[156:157], v[158:159]
	s_cmp_lt_u32 s16, 9
	s_cbranch_scc1 .Lfix_done
	s_waitcnt vmcnt(14)
	v_pk_fma_f32 v[2:3], v[2:3], v[160:161], v[162:163]
	s_cmp_lt_u32 s16, 10
	s_cbranch_scc1 .Lfix_done
	s_waitcnt vmcnt(12)
	v_pk_fma_f32 v[2:3], v[2:3], v[164:165], v[166:167]
	s_cmp_lt_u32 s16, 11
	s_cbranch_scc1 .Lfix_done
	s_waitcnt vmcnt(10)
	v_pk_fma_f32 v[2:3], v[2:3], v[168:169], v[170:171]
	s_cmp_lt_u32 s16, 12
	s_cbranch_scc1 .Lfix_done
	s_waitcnt vmcnt(8)
	v_pk_fma_f32 v[2:3], v[2:3], v[172:173], v[174:175]
	s_cmp_lt_u32 s16, 13
	s_cbranch_scc1 .Lfix_done
	s_waitcnt vmcnt(6)
	v_pk_fma_f32 v[2:3], v[2:3], v[176:177], v[178:179]
	s_cmp_lt_u32 s16, 14
	s_cbranch_scc1 .Lfix_done
	s_waitcnt vmcnt(4)
	v_pk_fma_f32 v[2:3], v[2:3], v[180:181], v[182:183]
	s_cmp_lt_u32 s16, 15
	s_cbranch_scc1 .Lfix_done
	s_waitcnt vmcnt(2)
	v_pk_fma_f32 v[2:3], v[2:3], v[184:185], v[186:187]
	s_cmp_lt_u32 s16, 16
	s_cbranch_scc1 .Lfix_done
	s_waitcnt vmcnt(0)
	v_pk_fma_f32 v[2:3], v[2:3], v[188:189], v[190:191]
	s_sub_u32 s16, s16, 16
	s_cmp_eq_u32 s16, 0
	s_cbranch_scc0 .Lfix_blk
.Lfix_done:
	s_waitcnt vmcnt(0)
.LBB0_2905:
	s_lshl_b32 s16, s40, 17
	s_and_b32 s41, s40, 0xbf
	s_cmp_eq_u32 s41, 63
	s_cselect_b64 s[42:43], -1, 0
	s_lshl_b32 s78, s40, 16
	s_lshl_b32 s40, s40, 6
	s_and_b32 s40, s40, 0x1000
	v_ashrrev_i32_e32 v7, 31, v6
	s_add_u32 s40, s3, s40
	s_addc_u32 s41, s23, 0
	v_lshlrev_b64 v[8:9], 2, v[6:7]
	v_lshlrev_b64 v[12:13], 1, v[6:7]
	s_mov_b32 s79, s17
	v_lshl_add_u64 v[4:5], s[40:41], 0, v[8:9]
	v_lshl_add_u64 v[6:7], s[16:17], 1, v[12:13]
	v_lshl_add_u64 v[8:9], s[78:79], 2, v[8:9]
	v_lshl_add_u64 v[12:13], v[12:13], 0, s[16:17]
	s_mov_b32 s16, -16
	s_xor_b64 s[40:41], s[42:43], -1
	s_branch .LBB0_2907

; __global__ void __launch_bounds__(NTHREADS, 2) mk_fwd(Params p) {
;     extern __shared__ __attribute__((aligned(16))) unsigned char lds_raw[];
	.amdhsa_kernel _ZN12_GLOBAL__N_16mk_fwdENS_6ParamsE
		.amdhsa_group_segment_fixed_size 0
		.amdhsa_private_segment_fixed_size 0
		.amdhsa_kernarg_size 504
		.amdhsa_user_sgpr_count 2
		.amdhsa_user_sgpr_dispatch_ptr 0
		.amdhsa_user_sgpr_queue_ptr 0
		.amdhsa_user_sgpr_kernarg_segment_ptr 1
		.amdhsa_user_sgpr_dispatch_id 0
		.amdhsa_user_sgpr_kernarg_preload_length 0
		.amdhsa_user_sgpr_kernarg_preload_offset 0
		.amdhsa_user_sgpr_private_segment_size 0
		.amdhsa_uses_dynamic_stack 0
		.amdhsa_enable_private_segment 0
		.amdhsa_system_sgpr_workgroup_id_x 1
		.amdhsa_system_sgpr_workgroup_id_y 0
		.amdhsa_system_sgpr_workgroup_id_z 0
		.amdhsa_system_sgpr_workgroup_info 0
		.amdhsa_system_vgpr_workitem_id 0
		.amdhsa_next_free_vgpr 256
		.amdhsa_next_free_sgpr 100
		.amdhsa_accum_offset 256
		.amdhsa_reserve_vcc 1
		.amdhsa_float_round_mode_32 0
		.amdhsa_float_round_mode_16_64 0
		.amdhsa_float_denorm_mode_32 3
		.amdhsa_float_denorm_mode_16_64 3
		.amdhsa_dx10_clamp 1
		.amdhsa_ieee_mode 1
		.amdhsa_fp16_overflow 0
		.amdhsa_tg_split 0
		.amdhsa_exception_fp_ieee_invalid_op 0
		.amdhsa_exception_fp_denorm_src 0
		.amdhsa_exception_fp_ieee_div_zero 0
		.amdhsa_exception_fp_ieee_overflow 0
		.amdhsa_exception_fp_ieee_underflow 0
		.amdhsa_exception_fp_ieee_inexact 0
		.amdhsa_exception_int_div_zero 0
	.end_amdhsa_kernel

; __global__ void __launch_bounds__(NTHREADS, 2) mk_fwd(Params p) {
;     extern __shared__ __attribute__((aligned(16))) unsigned char lds_raw[];
amdhsa.kernels:
  - .agpr_count:     0
    .args:
      - .offset:         0
        .size:           248
        .value_kind:     by_value
      - .offset:         248
        .size:           4
        .value_kind:     hidden_block_count_x
      - .offset:         252
        .size:           4
        .value_kind:     hidden_block_count_y
      - .offset:         256
        .size:           4
        .value_kind:     hidden_block_count_z
      - .offset:         260
        .size:           2
        .value_kind:     hidden_group_size_x
      - .offset:         262
        .size:           2
        .value_kind:     hidden_group_size_y
      - .offset:         264
        .size:           2
        .value_kind:     hidden_group_size_z
      - .offset:         266
        .size:           2
        .value_kind:     hidden_remainder_x
      - .offset:         268
        .size:           2
        .value_kind:     hidden_remainder_y
      - .offset:         270
        .size:           2
        .value_kind:     hidden_remainder_z
      - .offset:         288
        .size:           8
        .value_kind:     hidden_global_offset_x
      - .offset:         296
        .size:           8
        .value_kind:     hidden_global_offset_y
      - .offset:         304
        .size:           8
        .value_kind:     hidden_global_offset_z
      - .offset:         312
        .size:           2
        .value_kind:     hidden_grid_dims
      - .offset:         368
        .size:           4
        .value_kind:     hidden_dynamic_lds_size
    .group_segment_fixed_size: 0
    .kernarg_segment_align: 8
    .kernarg_segment_size: 504
    .language:       OpenCL C
    .language_version:
      - 2
      - 0
    .max_flat_workgroup_size: 512
    .name:           _ZN12_GLOBAL__N_16mk_fwdENS_6ParamsE
    .private_segment_fixed_size: 0
    .sgpr_count:     106
    .sgpr_spill_count: 91
    .symbol:         _ZN12_GLOBAL__N_16mk_fwdENS_6ParamsE.kd
    .uniform_work_group_size: 1
    .uses_dynamic_stack: false
    .vgpr_count:     256
    .vgpr_spill_count: 0
    .wavefront_size: 64
